# grid barrier: the acquire L1 invalidate is issued at arrival (after all waves drained, before the spin / alongside the L2 write-back) instead of after release, taking ~1.7us off every barrier's releas
# speedup vs baseline: 1.0070x; 1.0070x over previous
.LBB0_837:
	v_readlane_b32 s2, v254, 9
	v_readlane_b32 s3, v254, 10
	v_mov_b32_e32 v1, 1
	v_sub_u32_e32 v4, 0, v2
	s_nop 2
	global_atomic_add v3, v141, v1, s[2:3] sc0
	v_cvt_f32_u32_e32 v1, v2
	v_rcp_iflag_f32_e32 v1, v1
	s_nop 0
	v_mul_f32_e32 v1, 0x4f7ffffe, v1
	v_cvt_u32_f32_e32 v1, v1
	v_mul_lo_u32 v4, v4, v1
	v_mul_hi_u32 v4, v1, v4
	v_add_u32_e32 v1, v1, v4
	s_waitcnt vmcnt(0)
	v_mul_hi_u32 v1, v3, v1
	v_mul_lo_u32 v4, v1, v2
	v_sub_u32_e32 v4, v3, v4
	v_add_u32_e32 v5, 1, v1
	v_cmp_ge_u32_e32 vcc, v4, v2
	v_add_u32_e32 v3, 1, v3
	s_nop 0
	v_cndmask_b32_e32 v1, v1, v5, vcc
	v_sub_u32_e32 v5, v4, v2
	v_cndmask_b32_e32 v4, v4, v5, vcc
	v_add_u32_e32 v5, 1, v1
	v_cmp_ge_u32_e32 vcc, v4, v2
	s_nop 1
	v_cndmask_b32_e32 v1, v1, v5, vcc
	v_mul_lo_u32 v4, v2, v1
	v_add_u32_e32 v2, v4, v2
	v_cmp_ne_u32_e32 vcc, v3, v2
	s_and_saveexec_b64 s[6:7], vcc
	s_xor_b64 s[6:7], exec, s[6:7]
	s_cbranch_execz .LBB0_851
	v_readlane_b32 s2, v254, 11
	v_readlane_b32 s3, v254, 12
	s_waitcnt lgkmcnt(0)
	s_nop 3
	buffer_inv sc1
	global_load_dword v0, v141, s[2:3] sc1
	s_waitcnt vmcnt(0)
	v_cmp_eq_u32_e32 vcc, v0, v1
	s_and_saveexec_b64 s[8:9], vcc
	s_cbranch_execz .LBB0_850
	s_mov_b32 s4, 1
	s_mov_b64 s[10:11], 0
	s_branch .LBB0_841

.LBB0_850:
	s_or_b64 exec, exec, s[8:9]
	s_waitcnt vmcnt(0)
	s_waitcnt vmcnt(0)
.LBB0_851:
	s_andn2_saveexec_b64 s[6:7], s[6:7]
	s_cbranch_execz .LBB0_869
	s_mov_b64 s[6:7], exec
	buffer_wbl2 sc1
	buffer_inv sc1
	s_waitcnt lgkmcnt(0)
	s_waitcnt vmcnt(0)
	v_mbcnt_lo_u32_b32 v1, s6, 0
	v_mbcnt_hi_u32_b32 v1, s7, v1
	v_cmp_eq_u32_e32 vcc, 0, v1
	s_and_saveexec_b64 s[8:9], vcc
	s_cbranch_execz .LBB0_854
	s_bcnt1_i32_b64 s4, s[6:7]
	v_readlane_b32 s2, v254, 13
	v_mov_b32_e32 v2, s4
	v_readlane_b32 s3, v254, 14
	s_nop 4
	global_atomic_add v2, v141, v2, s[2:3] sc0

.LBB0_868:
	s_or_b64 exec, exec, s[6:7]
	v_readlane_b32 s2, v254, 11
	v_readlane_b32 s3, v254, 12
	v_mov_b32_e32 v0, 1
	s_waitcnt vmcnt(0)
	s_nop 3
	global_atomic_add v141, v0, s[2:3]
	s_waitcnt vmcnt(0)
